# gdn kk/qk products as plain v_fmac chains (no packed ops/shuffles), double-buffered fragment reads
# baseline (speedup 1.0000x reference)
; DI void gdn_chunk(CP c, int l, int item, float* sm) {
;     ...
;         const int wv = __builtin_amdgcn_readfirstlane(wave); const int njj = (8 * wv < C) ? wv + 1 : 0;
;         if (njj > 0) {
;             for (int d4 = 0; d4 < 32; ++d4) { const f32x4 ki = *(const f32x4*)(Ks + i * 132 + d4 * 4), qi = *(const f32x4*)(Qs + i * 132 + d4 * 4);
; #pragma unroll
;                 for (int jj = 0; jj < 8; ++jj) if (jj < njj) { const f32x4 kj = *(const f32x4*)(Ks + (t7 + 8 * jj) * 132 + d4 * 4);
;                     kk[jj] += ki[0] * kj[0] + ki[1] * kj[1] + ki[2] * kj[2] + ki[3] * kj[3]; qk[jj] += qi[0] * kj[0] + qi[1] * kj[1] + qi[2] * kj[2] + qi[3] * kj[3]; } }
;         }
.Lkk_ld_b:
	s_andn2_b64 vcc, exec, s[6:7]
	s_cbranch_vccnz .Lkk_j0_a
	v_fmac_f32_e32 v28, v10, v40
	v_fmac_f32_e32 v29, v2, v40
	v_fmac_f32_e32 v28, v11, v41
	v_fmac_f32_e32 v29, v3, v41
	v_fmac_f32_e32 v28, v12, v42
	v_fmac_f32_e32 v29, v4, v42
	v_fmac_f32_e32 v28, v13, v43
	v_fmac_f32_e32 v29, v5, v43
	s_andn2_b64 vcc, exec, s[12:13]
	s_cbranch_vccnz .Lkk_j0_a
	v_fmac_f32_e32 v26, v10, v44
	v_fmac_f32_e32 v27, v2, v44
	v_fmac_f32_e32 v26, v11, v45
	v_fmac_f32_e32 v27, v3, v45
	v_fmac_f32_e32 v26, v12, v46
	v_fmac_f32_e32 v27, v4, v46
	v_fmac_f32_e32 v26, v13, v47
	v_fmac_f32_e32 v27, v5, v47
	s_andn2_b64 vcc, exec, s[24:25]
	s_cbranch_vccnz .Lkk_j0_a
	v_fmac_f32_e32 v24, v10, v48
	v_fmac_f32_e32 v25, v2, v48
	v_fmac_f32_e32 v24, v11, v49
	v_fmac_f32_e32 v25, v3, v49
	v_fmac_f32_e32 v24, v12, v50
	v_fmac_f32_e32 v25, v4, v50
	v_fmac_f32_e32 v24, v13, v51
	v_fmac_f32_e32 v25, v5, v51
	s_andn2_b64 vcc, exec, s[26:27]
	s_cbranch_vccnz .Lkk_j0_a
	v_fmac_f32_e32 v22, v10, v52
	v_fmac_f32_e32 v23, v2, v52
	v_fmac_f32_e32 v22, v11, v53
	v_fmac_f32_e32 v23, v3, v53
	v_fmac_f32_e32 v22, v12, v54
	v_fmac_f32_e32 v23, v4, v54
	v_fmac_f32_e32 v22, v13, v55
	v_fmac_f32_e32 v23, v5, v55
	s_andn2_b64 vcc, exec, s[28:29]
	s_cbranch_vccnz .Lkk_j0_a
	v_fmac_f32_e32 v20, v10, v56
	v_fmac_f32_e32 v21, v2, v56
	v_fmac_f32_e32 v20, v11, v57
	v_fmac_f32_e32 v21, v3, v57
	v_fmac_f32_e32 v20, v12, v58
	v_fmac_f32_e32 v21, v4, v58
	v_fmac_f32_e32 v20, v13, v59
	v_fmac_f32_e32 v21, v5, v59
	s_andn2_b64 vcc, exec, s[30:31]
	s_cbranch_vccnz .Lkk_j0_a
	v_fmac_f32_e32 v18, v10, v60
	v_fmac_f32_e32 v19, v2, v60
	v_fmac_f32_e32 v18, v11, v61
	v_fmac_f32_e32 v19, v3, v61
	v_fmac_f32_e32 v18, v12, v62
	v_fmac_f32_e32 v19, v4, v62
	v_fmac_f32_e32 v18, v13, v63
	v_fmac_f32_e32 v19, v5, v63
	s_andn2_b64 vcc, exec, s[34:35]
	s_cbranch_vccnz .Lkk_j0_a
	v_fmac_f32_e32 v16, v10, v64
	v_fmac_f32_e32 v17, v2, v64
	v_fmac_f32_e32 v16, v11, v65
	v_fmac_f32_e32 v17, v3, v65
	v_fmac_f32_e32 v16, v12, v66
	v_fmac_f32_e32 v17, v4, v66
	v_fmac_f32_e32 v16, v13, v67
	v_fmac_f32_e32 v17, v5, v67
.Lkk_j0_a:
	v_fmac_f32_e32 v30, v10, v6
	v_fmac_f32_e32 v31, v2, v6
	v_fmac_f32_e32 v30, v11, v7
	v_fmac_f32_e32 v31, v3, v7
	v_fmac_f32_e32 v30, v12, v8
	v_fmac_f32_e32 v31, v4, v8
	v_fmac_f32_e32 v30, v13, v9
	v_fmac_f32_e32 v31, v5, v9
	s_waitcnt lgkmcnt(0)
	s_add_i32 s0, s0, 32
	s_cmpk_lg_i32 s0, 0x200
	s_cbranch_scc0 .Lkk_last
	v_add_u32_e32 v6, s0, v0
	ds_read_b128 v[2:5], v6
	ds_read_b128 v[10:13], v6 offset:33792
	v_add_u32_e32 v35, s0, v15
	ds_read_b128 v[6:9], v35
	s_andn2_b64 vcc, exec, s[6:7]
	s_cbranch_vccnz .Lkk_ld_a2
	ds_read_b128 v[40:43], v35 offset:4224
	s_andn2_b64 vcc, exec, s[12:13]
	s_cbranch_vccnz .Lkk_ld_a2
	ds_read_b128 v[44:47], v35 offset:8448
	s_andn2_b64 vcc, exec, s[24:25]
	s_cbranch_vccnz .Lkk_ld_a2
	ds_read_b128 v[48:51], v35 offset:12672
	s_andn2_b64 vcc, exec, s[26:27]
	s_cbranch_vccnz .Lkk_ld_a2
	ds_read_b128 v[52:55], v35 offset:16896
	s_andn2_b64 vcc, exec, s[28:29]
	s_cbranch_vccnz .Lkk_ld_a2
	ds_read_b128 v[56:59], v35 offset:21120
	s_andn2_b64 vcc, exec, s[30:31]
	s_cbranch_vccnz .Lkk_ld_a2
	ds_read_b128 v[60:63], v35 offset:25344
	s_andn2_b64 vcc, exec, s[34:35]
	s_cbranch_vccnz .Lkk_ld_a2
	ds_read_b128 v[64:67], v35 offset:29568
.Lkk_ld_a2:
	s_andn2_b64 vcc, exec, s[6:7]
	s_cbranch_vccnz .Lkk_j0_b
	v_fmac_f32_e32 v28, v86, v94
	v_fmac_f32_e32 v29, v82, v94
	v_fmac_f32_e32 v28, v87, v95
	v_fmac_f32_e32 v29, v83, v95
	v_fmac_f32_e32 v28, v88, v96
	v_fmac_f32_e32 v29, v84, v96
	v_fmac_f32_e32 v28, v89, v97
	v_fmac_f32_e32 v29, v85, v97
	s_andn2_b64 vcc, exec, s[12:13]
	s_cbranch_vccnz .Lkk_j0_b
	v_fmac_f32_e32 v26, v86, v98
	v_fmac_f32_e32 v27, v82, v98
	v_fmac_f32_e32 v26, v87, v99
	v_fmac_f32_e32 v27, v83, v99
	v_fmac_f32_e32 v26, v88, v100
	v_fmac_f32_e32 v27, v84, v100
	v_fmac_f32_e32 v26, v89, v101
	v_fmac_f32_e32 v27, v85, v101
	s_andn2_b64 vcc, exec, s[24:25]
	s_cbranch_vccnz .Lkk_j0_b
	v_fmac_f32_e32 v24, v86, v102
	v_fmac_f32_e32 v25, v82, v102
	v_fmac_f32_e32 v24, v87, v103
	v_fmac_f32_e32 v25, v83, v103
	v_fmac_f32_e32 v24, v88, v104
	v_fmac_f32_e32 v25, v84, v104
	v_fmac_f32_e32 v24, v89, v105
	v_fmac_f32_e32 v25, v85, v105
	s_andn2_b64 vcc, exec, s[26:27]
	s_cbranch_vccnz .Lkk_j0_b
	v_fmac_f32_e32 v22, v86, v106
	v_fmac_f32_e32 v23, v82, v106
	v_fmac_f32_e32 v22, v87, v107
	v_fmac_f32_e32 v23, v83, v107
	v_fmac_f32_e32 v22, v88, v108
	v_fmac_f32_e32 v23, v84, v108
	v_fmac_f32_e32 v22, v89, v109
	v_fmac_f32_e32 v23, v85, v109
	s_andn2_b64 vcc, exec, s[28:29]
	s_cbranch_vccnz .Lkk_j0_b
	v_fmac_f32_e32 v20, v86, v110
	v_fmac_f32_e32 v21, v82, v110
	v_fmac_f32_e32 v20, v87, v111
	v_fmac_f32_e32 v21, v83, v111
	v_fmac_f32_e32 v20, v88, v112
	v_fmac_f32_e32 v21, v84, v112
	v_fmac_f32_e32 v20, v89, v113
	v_fmac_f32_e32 v21, v85, v113
	s_andn2_b64 vcc, exec, s[30:31]
	s_cbranch_vccnz .Lkk_j0_b
	v_fmac_f32_e32 v18, v86, v114
	v_fmac_f32_e32 v19, v82, v114
	v_fmac_f32_e32 v18, v87, v115
	v_fmac_f32_e32 v19, v83, v115
	v_fmac_f32_e32 v18, v88, v116
	v_fmac_f32_e32 v19, v84, v116
	v_fmac_f32_e32 v18, v89, v117
	v_fmac_f32_e32 v19, v85, v117
	s_andn2_b64 vcc, exec, s[34:35]
	s_cbranch_vccnz .Lkk_j0_b
	v_fmac_f32_e32 v16, v86, v118
	v_fmac_f32_e32 v17, v82, v118
	v_fmac_f32_e32 v16, v87, v119
	v_fmac_f32_e32 v17, v83, v119
	v_fmac_f32_e32 v16, v88, v120
	v_fmac_f32_e32 v17, v84, v120
	v_fmac_f32_e32 v16, v89, v121
	v_fmac_f32_e32 v17, v85, v121
.Lkk_j0_b:
	v_fmac_f32_e32 v30, v86, v90
	v_fmac_f32_e32 v31, v82, v90
	v_fmac_f32_e32 v30, v87, v91
	v_fmac_f32_e32 v31, v83, v91
	v_fmac_f32_e32 v30, v88, v92
	v_fmac_f32_e32 v31, v84, v92
	v_fmac_f32_e32 v30, v89, v93
	v_fmac_f32_e32 v31, v85, v93
	s_branch .Lkk_loop
